# v13 + 64-byte alignment of the six hot loop heads (code placement only)
# baseline (speedup 1.0000x reference)
.LBB0_39:
	s_or_b64 exec, exec, s[30:31]
	s_add_i32 s29, s41, s34
	s_min_i32 s48, s29, s67
	s_cmp_ge_i32 s92, s48
	s_cbranch_scc1 .LBB0_36
	v_mad_i64_i32 v[66:67], s[30:31], v88, s85, 0
	v_mad_i64_i32 v[68:69], s[30:31], v89, s85, 0
	s_ashr_i32 s29, s28, 31
	s_lshl_b64 s[30:31], s[28:29], 2
	s_sub_i32 s29, s40, s34
	s_add_i32 s49, s42, s34
	v_and_b32_e32 v0, 7, v0
	s_lshl_b32 s34, s92, 1
	v_lshlrev_b32_e32 v0, 4, v0
	s_add_u32 s34, s45, s34
	v_lshl_add_u64 v[68:69], v[68:69], 0, v[0:1]
	s_addc_u32 s35, s46, 0
	v_lshl_add_u64 v[66:67], v[66:67], 0, v[0:1]
	v_lshl_add_u64 v[158:159], s[34:35], 0, v[68:69]
	v_lshl_add_u64 v[160:161], s[34:35], 0, v[66:67]
	s_lshl_b64 s[34:35], s[92:93], 2
	s_add_u32 s30, s30, s34
	s_addc_u32 s31, s31, s35
	v_lshl_add_u64 v[154:155], v[82:83], 1, s[26:27]
	v_lshl_add_u64 v[156:157], v[84:85], 1, s[26:27]
	v_add_u32_e32 v175, 64, v87
	v_add_u32_e32 v176, 64, v86
	v_lshl_add_u64 v[162:163], v[150:151], 0, s[30:31]
	s_mov_b32 s50, 0
	.p2align 6

.LBB0_66:
	v_lshl_add_u64 v[150:151], v[150:151], 0, s[20:21]
	v_lshl_add_u64 v[152:153], v[152:153], 0, s[20:21]
	v_lshl_add_u64 v[154:155], v[154:155], 0, s[44:45]
	v_lshl_add_u64 v[156:157], v[156:157], 0, s[44:45]
	s_andn2_b64 vcc, exec, s[26:27]
	s_add_i32 s34, s34, 64
	s_waitcnt lgkmcnt(0)
	s_barrier
	s_cbranch_vccz .LBB0_73
	.p2align 6

.LBB0_90:
	v_lshl_add_u64 v[198:199], v[198:199], 0, s[20:21]
	v_lshl_add_u64 v[196:197], v[196:197], 0, s[20:21]
	s_add_i32 s45, s45, 64
	v_lshl_add_u64 v[200:201], v[200:201], 0, s[50:51]
	v_lshl_add_u64 v[202:203], v[202:203], 0, s[50:51]
	s_andn2_b64 vcc, exec, s[34:35]
	v_lshl_add_u64 v[204:205], v[204:205], 0, s[74:75]
	s_waitcnt lgkmcnt(0)
	s_barrier
	s_cbranch_vccz .LBB0_102
	.p2align 6

.LBB0_108:
	v_lshl_add_u64 v[170:171], v[170:171], 0, s[20:21]
	v_lshl_add_u64 v[172:173], v[172:173], 0, s[20:21]
	v_lshl_add_u64 v[174:175], v[174:175], 0, s[34:35]
	v_lshl_add_u64 v[176:177], v[176:177], 0, s[34:35]
	v_lshl_add_u64 v[178:179], v[178:179], 0, s[34:35]
	s_andn2_b64 vcc, exec, s[24:25]
	s_add_i32 s30, s30, 64
	s_waitcnt lgkmcnt(0)
	s_barrier
	s_cbranch_vccz .LBB0_115
	.p2align 6

.LBB0_177:
	s_add_u32 s0, s14, 0x80
	s_addc_u32 s1, s15, 0
	s_add_u32 s42, s44, 0x100
	s_addc_u32 s43, s45, 0
	s_mov_b32 s14, 0
	v_add_u32_e32 v248, 0x10000, v234
	v_add_u32_e32 v242, s64, v0
	v_add_u32_e32 v249, s64, v176
	v_add_u32_e32 v204, 0x80, v0
	v_add_u32_e32 v205, 0x80, v176
	v_add_u32_e32 v220, 0x80, v172
	v_add_u32_e32 v221, 0x80, v174
	v_add_u32_e32 v218, 0x80, v242
	v_add_u32_e32 v219, 0x80, v249
	s_waitcnt vmcnt(0)
	.p2align 6
.Lk_peel:
	s_add_i32 s44, s14, 2
	s_add_u32 s45, s0, 0x80
	s_addc_u32 s15, s1, 0
	s_add_i32 s57, 0, 0x10000
	s_cmp_eq_u32 s18, s14
	s_cselect_b32 s15, s89, s15
	s_cselect_b32 s14, s88, s45
	s_cselect_b32 vcc_hi, s11, s43
	s_cselect_b32 vcc_lo, s10, s42
	s_add_i32 s45, 0, 0x14000
	s_waitcnt lgkmcnt(0)
	ds_read_b128 v[130:133], v248
	ds_read_b128 v[134:137], v248 offset:1024
	ds_read_b128 v[138:141], v248 offset:2048
	ds_read_b128 v[142:145], v248 offset:3072
	ds_read_b128 v[146:149], v248 offset:16384
	ds_read_b128 v[150:153], v248 offset:17408
	ds_read_b128 v[154:157], v248 offset:18432
	ds_read_b128 v[158:161], v248 offset:19456
	s_add_i32 m0, s70, 0xc000
	ds_read_b128 v[162:165], v237
	ds_read_b128 v[166:169], v237 offset:1024
	ds_read_b128 v[184:187], v237 offset:2048
	ds_read_b128 v[188:191], v237 offset:3072
	ds_read_b128 v[192:195], v237 offset:4096
	ds_read_b128 v[196:199], v237 offset:5120
	ds_read_b128 v[200:203], v237 offset:6144
	ds_read_b128 v[214:217], v237 offset:7168
	global_load_lds_dwordx4 v180, s[0:1]
	s_add_i32 m0, s70, 0xe000
	s_nop 0
	global_load_lds_dwordx4 v182, s[0:1]
	s_waitcnt vmcnt(8)
	s_waitcnt lgkmcnt(0)
	s_barrier
	s_setprio 1
	s_waitcnt lgkmcnt(0)
	v_mfma_f32_16x16x32_bf16 v[122:125], v[130:133], v[162:165], 0
	v_mfma_f32_16x16x32_bf16 v[126:129], v[138:141], v[162:165], 0
	v_mfma_f32_16x16x32_bf16 v[106:109], v[130:133], v[184:187], 0
	v_mfma_f32_16x16x32_bf16 v[110:113], v[138:141], v[184:187], 0
	v_mfma_f32_16x16x32_bf16 v[90:93], v[130:133], v[192:195], 0
	v_mfma_f32_16x16x32_bf16 v[94:97], v[138:141], v[192:195], 0
	v_mfma_f32_16x16x32_bf16 v[74:77], v[130:133], v[200:203], 0
	v_mfma_f32_16x16x32_bf16 v[78:81], v[138:141], v[200:203], 0
	v_mfma_f32_16x16x32_bf16 v[122:125], v[134:137], v[166:169], v[122:125]
	v_mfma_f32_16x16x32_bf16 v[126:129], v[142:145], v[166:169], v[126:129]
	v_mfma_f32_16x16x32_bf16 v[106:109], v[134:137], v[188:191], v[106:109]
	v_mfma_f32_16x16x32_bf16 v[110:113], v[142:145], v[188:191], v[110:113]
	v_mfma_f32_16x16x32_bf16 v[90:93], v[134:137], v[196:199], v[90:93]
	v_mfma_f32_16x16x32_bf16 v[94:97], v[142:145], v[196:199], v[94:97]
	v_mfma_f32_16x16x32_bf16 v[74:77], v[134:137], v[214:217], v[74:77]
	v_mfma_f32_16x16x32_bf16 v[78:81], v[142:145], v[214:217], v[78:81]
	v_mfma_f32_16x16x32_bf16 v[114:117], v[146:149], v[162:165], 0
	v_mfma_f32_16x16x32_bf16 v[118:121], v[154:157], v[162:165], 0
	v_mfma_f32_16x16x32_bf16 v[98:101], v[146:149], v[184:187], 0
	v_mfma_f32_16x16x32_bf16 v[102:105], v[154:157], v[184:187], 0
	v_mfma_f32_16x16x32_bf16 v[82:85], v[146:149], v[192:195], 0
	v_mfma_f32_16x16x32_bf16 v[86:89], v[154:157], v[192:195], 0
	v_mfma_f32_16x16x32_bf16 v[66:69], v[146:149], v[200:203], 0
	v_mfma_f32_16x16x32_bf16 v[70:73], v[154:157], v[200:203], 0
	v_mfma_f32_16x16x32_bf16 v[114:117], v[150:153], v[166:169], v[114:117]
	v_mfma_f32_16x16x32_bf16 v[118:121], v[158:161], v[166:169], v[118:121]
	v_mfma_f32_16x16x32_bf16 v[98:101], v[150:153], v[188:191], v[98:101]
	v_mfma_f32_16x16x32_bf16 v[102:105], v[158:161], v[188:191], v[102:105]
	v_mfma_f32_16x16x32_bf16 v[82:85], v[150:153], v[196:199], v[82:85]
	v_mfma_f32_16x16x32_bf16 v[86:89], v[158:161], v[196:199], v[86:89]
	v_mfma_f32_16x16x32_bf16 v[66:69], v[150:153], v[214:217], v[66:69]
	v_mfma_f32_16x16x32_bf16 v[70:73], v[158:161], v[214:217], v[70:73]
	s_setprio 0
	s_barrier
	s_add_i32 s57, s57, s59
	s_mov_b32 m0, s57
	ds_read_b128 v[162:165], v237 offset:16384
	ds_read_b128 v[166:169], v237 offset:17408
	ds_read_b128 v[184:187], v237 offset:18432
	ds_read_b128 v[188:191], v237 offset:19456
	ds_read_b128 v[192:195], v237 offset:20480
	ds_read_b128 v[196:199], v237 offset:21504
	ds_read_b128 v[200:203], v237 offset:22528
	ds_read_b128 v[214:217], v237 offset:23552
	global_load_lds_dwordx4 v0, vcc
	s_add_i32 m0, s57, 0x2000
	s_add_i32 s45, s45, s59
	global_load_lds_dwordx4 v176, vcc
	s_mov_b32 m0, s45
	s_nop 0
	global_load_lds_dwordx4 v242, vcc
	s_add_i32 m0, s45, 0x2000
	s_nop 0
	global_load_lds_dwordx4 v249, vcc
	s_mov_b32 m0, s70
	s_nop 0
	global_load_lds_dwordx4 v172, s[14:15]
	s_mov_b32 m0, s4
	s_nop 0
	global_load_lds_dwordx4 v174, s[14:15]
	s_waitcnt vmcnt(8)
	s_waitcnt lgkmcnt(0)
	s_barrier
	s_setprio 1
	s_waitcnt lgkmcnt(0)
	v_mfma_f32_16x16x32_bf16 v[58:61], v[130:133], v[162:165], 0
	v_mfma_f32_16x16x32_bf16 v[62:65], v[138:141], v[162:165], 0
	v_mfma_f32_16x16x32_bf16 v[42:45], v[130:133], v[184:187], 0
	v_mfma_f32_16x16x32_bf16 v[46:49], v[138:141], v[184:187], 0
	v_mfma_f32_16x16x32_bf16 v[26:29], v[130:133], v[192:195], 0
	v_mfma_f32_16x16x32_bf16 v[30:33], v[138:141], v[192:195], 0
	v_mfma_f32_16x16x32_bf16 v[10:13], v[130:133], v[200:203], 0
	v_mfma_f32_16x16x32_bf16 v[14:17], v[138:141], v[200:203], 0
	v_mfma_f32_16x16x32_bf16 v[58:61], v[134:137], v[166:169], v[58:61]
	v_mfma_f32_16x16x32_bf16 v[62:65], v[142:145], v[166:169], v[62:65]
	v_mfma_f32_16x16x32_bf16 v[42:45], v[134:137], v[188:191], v[42:45]
	v_mfma_f32_16x16x32_bf16 v[46:49], v[142:145], v[188:191], v[46:49]
	v_mfma_f32_16x16x32_bf16 v[26:29], v[134:137], v[196:199], v[26:29]
	v_mfma_f32_16x16x32_bf16 v[30:33], v[142:145], v[196:199], v[30:33]
	v_mfma_f32_16x16x32_bf16 v[10:13], v[134:137], v[214:217], v[10:13]
	v_mfma_f32_16x16x32_bf16 v[14:17], v[142:145], v[214:217], v[14:17]
	v_mfma_f32_16x16x32_bf16 v[50:53], v[146:149], v[162:165], 0
	v_mfma_f32_16x16x32_bf16 v[54:57], v[154:157], v[162:165], 0
	v_mfma_f32_16x16x32_bf16 v[34:37], v[146:149], v[184:187], 0
	v_mfma_f32_16x16x32_bf16 v[38:41], v[154:157], v[184:187], 0
	v_mfma_f32_16x16x32_bf16 v[18:21], v[146:149], v[192:195], 0
	v_mfma_f32_16x16x32_bf16 v[22:25], v[154:157], v[192:195], 0
	v_mfma_f32_16x16x32_bf16 v[6:9], v[146:149], v[200:203], 0
	v_mfma_f32_16x16x32_bf16 v[2:5], v[154:157], v[200:203], 0
	v_mfma_f32_16x16x32_bf16 v[50:53], v[150:153], v[166:169], v[50:53]
	v_mfma_f32_16x16x32_bf16 v[54:57], v[158:161], v[166:169], v[54:57]
	v_mfma_f32_16x16x32_bf16 v[34:37], v[150:153], v[188:191], v[34:37]
	v_mfma_f32_16x16x32_bf16 v[38:41], v[158:161], v[188:191], v[38:41]
	v_mfma_f32_16x16x32_bf16 v[18:21], v[150:153], v[196:199], v[18:21]
	v_mfma_f32_16x16x32_bf16 v[22:25], v[158:161], v[196:199], v[22:25]
	v_mfma_f32_16x16x32_bf16 v[6:9], v[150:153], v[214:217], v[6:9]
	v_mfma_f32_16x16x32_bf16 v[2:5], v[158:161], v[214:217], v[2:5]
	s_setprio 0
	s_barrier
	s_add_i32 s45, 0, 0x18000
	s_add_i32 s57, 0, 0x1c000
	ds_read_b128 v[130:133], v248 offset:32768
	ds_read_b128 v[134:137], v248 offset:33792
	ds_read_b128 v[138:141], v248 offset:34816
	ds_read_b128 v[142:145], v248 offset:35840
	ds_read_b128 v[146:149], v248 offset:49152
	ds_read_b128 v[150:153], v248 offset:50176
	ds_read_b128 v[154:157], v248 offset:51200
	ds_read_b128 v[158:161], v248 offset:52224
	s_mov_b32 m0, s63
	ds_read_b128 v[162:165], v237 offset:32768
	ds_read_b128 v[166:169], v237 offset:33792
	ds_read_b128 v[184:187], v237 offset:34816
	ds_read_b128 v[188:191], v237 offset:35840
	ds_read_b128 v[192:195], v237 offset:36864
	ds_read_b128 v[196:199], v237 offset:37888
	ds_read_b128 v[200:203], v237 offset:38912
	ds_read_b128 v[214:217], v237 offset:39936
	global_load_lds_dwordx4 v180, s[14:15]
	s_mov_b32 m0, s68
	s_nop 0
	global_load_lds_dwordx4 v182, s[14:15]
	s_waitcnt vmcnt(8)
	s_waitcnt lgkmcnt(0)
	s_barrier
	s_setprio 1
	s_waitcnt lgkmcnt(0)
	v_mfma_f32_16x16x32_bf16 v[122:125], v[130:133], v[162:165], v[122:125]
	v_mfma_f32_16x16x32_bf16 v[126:129], v[138:141], v[162:165], v[126:129]
	v_mfma_f32_16x16x32_bf16 v[106:109], v[130:133], v[184:187], v[106:109]
	v_mfma_f32_16x16x32_bf16 v[110:113], v[138:141], v[184:187], v[110:113]
	v_mfma_f32_16x16x32_bf16 v[90:93], v[130:133], v[192:195], v[90:93]
	v_mfma_f32_16x16x32_bf16 v[94:97], v[138:141], v[192:195], v[94:97]
	v_mfma_f32_16x16x32_bf16 v[74:77], v[130:133], v[200:203], v[74:77]
	v_mfma_f32_16x16x32_bf16 v[78:81], v[138:141], v[200:203], v[78:81]
	v_mfma_f32_16x16x32_bf16 v[122:125], v[134:137], v[166:169], v[122:125]
	v_mfma_f32_16x16x32_bf16 v[126:129], v[142:145], v[166:169], v[126:129]
	v_mfma_f32_16x16x32_bf16 v[106:109], v[134:137], v[188:191], v[106:109]
	v_mfma_f32_16x16x32_bf16 v[110:113], v[142:145], v[188:191], v[110:113]
	v_mfma_f32_16x16x32_bf16 v[90:93], v[134:137], v[196:199], v[90:93]
	v_mfma_f32_16x16x32_bf16 v[94:97], v[142:145], v[196:199], v[94:97]
	v_mfma_f32_16x16x32_bf16 v[74:77], v[134:137], v[214:217], v[74:77]
	v_mfma_f32_16x16x32_bf16 v[78:81], v[142:145], v[214:217], v[78:81]
	v_mfma_f32_16x16x32_bf16 v[114:117], v[146:149], v[162:165], v[114:117]
	v_mfma_f32_16x16x32_bf16 v[118:121], v[154:157], v[162:165], v[118:121]
	v_mfma_f32_16x16x32_bf16 v[98:101], v[146:149], v[184:187], v[98:101]
	v_mfma_f32_16x16x32_bf16 v[102:105], v[154:157], v[184:187], v[102:105]
	v_mfma_f32_16x16x32_bf16 v[82:85], v[146:149], v[192:195], v[82:85]
	v_mfma_f32_16x16x32_bf16 v[86:89], v[154:157], v[192:195], v[86:89]
	v_mfma_f32_16x16x32_bf16 v[66:69], v[146:149], v[200:203], v[66:69]
	v_mfma_f32_16x16x32_bf16 v[70:73], v[154:157], v[200:203], v[70:73]
	v_mfma_f32_16x16x32_bf16 v[114:117], v[150:153], v[166:169], v[114:117]
	v_mfma_f32_16x16x32_bf16 v[118:121], v[158:161], v[166:169], v[118:121]
	v_mfma_f32_16x16x32_bf16 v[98:101], v[150:153], v[188:191], v[98:101]
	v_mfma_f32_16x16x32_bf16 v[102:105], v[158:161], v[188:191], v[102:105]
	v_mfma_f32_16x16x32_bf16 v[82:85], v[150:153], v[196:199], v[82:85]
	v_mfma_f32_16x16x32_bf16 v[86:89], v[158:161], v[196:199], v[86:89]
	v_mfma_f32_16x16x32_bf16 v[66:69], v[150:153], v[214:217], v[66:69]
	v_mfma_f32_16x16x32_bf16 v[70:73], v[158:161], v[214:217], v[70:73]
	s_setprio 0
	s_barrier
	s_add_i32 m0, s45, s59
	ds_read_b128 v[162:165], v237 offset:49152
	ds_read_b128 v[166:169], v237 offset:50176
	ds_read_b128 v[184:187], v237 offset:51200
	ds_read_b128 v[188:191], v237 offset:52224
	ds_read_b128 v[192:195], v237 offset:53248
	ds_read_b128 v[196:199], v237 offset:54272
	ds_read_b128 v[200:203], v237 offset:55296
	ds_read_b128 v[214:217], v237 offset:56320
	global_load_lds_dwordx4 v204, vcc
	s_add_i32 m0, m0, 0x2000
	s_nop 0
	global_load_lds_dwordx4 v205, vcc
	s_add_i32 m0, s57, s59
	s_nop 0
	global_load_lds_dwordx4 v218, vcc
	s_add_i32 m0, m0, 0x2000
	s_nop 0
	global_load_lds_dwordx4 v219, vcc
	s_mov_b32 m0, s67
	s_nop 0
	global_load_lds_dwordx4 v220, s[14:15]
	s_mov_b32 m0, s7
	s_nop 0
	global_load_lds_dwordx4 v221, s[14:15]
	s_waitcnt vmcnt(8)
	s_waitcnt lgkmcnt(0)
	s_barrier
	s_setprio 1
	s_waitcnt lgkmcnt(0)
	v_mfma_f32_16x16x32_bf16 v[58:61], v[130:133], v[162:165], v[58:61]
	v_mfma_f32_16x16x32_bf16 v[62:65], v[138:141], v[162:165], v[62:65]
	v_mfma_f32_16x16x32_bf16 v[42:45], v[130:133], v[184:187], v[42:45]
	v_mfma_f32_16x16x32_bf16 v[46:49], v[138:141], v[184:187], v[46:49]
	v_mfma_f32_16x16x32_bf16 v[26:29], v[130:133], v[192:195], v[26:29]
	v_mfma_f32_16x16x32_bf16 v[30:33], v[138:141], v[192:195], v[30:33]
	v_mfma_f32_16x16x32_bf16 v[10:13], v[130:133], v[200:203], v[10:13]
	v_mfma_f32_16x16x32_bf16 v[14:17], v[138:141], v[200:203], v[14:17]
	v_mfma_f32_16x16x32_bf16 v[58:61], v[134:137], v[166:169], v[58:61]
	v_mfma_f32_16x16x32_bf16 v[62:65], v[142:145], v[166:169], v[62:65]
	v_mfma_f32_16x16x32_bf16 v[42:45], v[134:137], v[188:191], v[42:45]
	v_mfma_f32_16x16x32_bf16 v[46:49], v[142:145], v[188:191], v[46:49]
	v_mfma_f32_16x16x32_bf16 v[26:29], v[134:137], v[196:199], v[26:29]
	v_mfma_f32_16x16x32_bf16 v[30:33], v[142:145], v[196:199], v[30:33]
	v_mfma_f32_16x16x32_bf16 v[10:13], v[134:137], v[214:217], v[10:13]
	v_mfma_f32_16x16x32_bf16 v[14:17], v[142:145], v[214:217], v[14:17]
	v_mfma_f32_16x16x32_bf16 v[50:53], v[146:149], v[162:165], v[50:53]
	v_mfma_f32_16x16x32_bf16 v[54:57], v[154:157], v[162:165], v[54:57]
	v_mfma_f32_16x16x32_bf16 v[34:37], v[146:149], v[184:187], v[34:37]
	v_mfma_f32_16x16x32_bf16 v[38:41], v[154:157], v[184:187], v[38:41]
	v_mfma_f32_16x16x32_bf16 v[18:21], v[146:149], v[192:195], v[18:21]
	v_mfma_f32_16x16x32_bf16 v[22:25], v[154:157], v[192:195], v[22:25]
	v_mfma_f32_16x16x32_bf16 v[6:9], v[146:149], v[200:203], v[6:9]
	v_mfma_f32_16x16x32_bf16 v[2:5], v[154:157], v[200:203], v[2:5]
	v_mfma_f32_16x16x32_bf16 v[50:53], v[150:153], v[166:169], v[50:53]
	v_mfma_f32_16x16x32_bf16 v[54:57], v[158:161], v[166:169], v[54:57]
	v_mfma_f32_16x16x32_bf16 v[34:37], v[150:153], v[188:191], v[34:37]
	v_mfma_f32_16x16x32_bf16 v[38:41], v[158:161], v[188:191], v[38:41]
	v_mfma_f32_16x16x32_bf16 v[18:21], v[150:153], v[196:199], v[18:21]
	v_mfma_f32_16x16x32_bf16 v[22:25], v[158:161], v[196:199], v[22:25]
	v_mfma_f32_16x16x32_bf16 v[6:9], v[150:153], v[214:217], v[6:9]
	v_mfma_f32_16x16x32_bf16 v[2:5], v[158:161], v[214:217], v[2:5]
	s_setprio 0
	s_barrier
	s_add_u32 s0, s0, 0x100
	s_addc_u32 s1, s1, 0
	s_add_u32 s42, s42, 0x100
	s_addc_u32 s43, s43, 0
	s_cmp_ge_u32 s44, s61
	s_mov_b32 s14, s44
	s_cbranch_scc1 .Lk_exit
	.p2align 6
